# attention inner loop: K/V fragment prefetch with independent accumulators interleaved (QK: S0/S1 alternate; PV: 4 output tiles round-robin) to avoid dependent back-to-back MFMA stalls
# speedup vs baseline: 1.1256x; 1.0013x over previous
.LBB0_267:
	s_bitcmp1_b32 s4, 0
	s_cselect_b32 s5, 0x8c00, 0
	v_xor_b32_e32 v66, 0x80000000, v154
	s_setprio 1
	v_or_b32_e32 v67, s5, v146
	v_add_u32_e32 v172, v67, v183
	ds_read_b128 v[206:209], v172
	ds_read_b128 v[210:213], v172 offset:4608
	ds_read_b128 v[222:225], v172 offset:32
	ds_read_b128 v[238:241], v172 offset:4640
	ds_read_b128 v[242:245], v172 offset:64
	v_mov_b32_e32 v67, v66
	v_mov_b32_e32 v68, v66
	v_mov_b32_e32 v69, v66
	v_mov_b32_e32 v70, v66
	v_mov_b32_e32 v71, v66
	v_mov_b32_e32 v72, v66
	v_mov_b32_e32 v73, v66
	v_mov_b32_e32 v74, v66
	v_mov_b32_e32 v75, v66
	v_mov_b32_e32 v76, v66
	v_mov_b32_e32 v77, v66
	v_mov_b32_e32 v78, v66
	v_mov_b32_e32 v79, v66
	v_mov_b32_e32 v80, v66
	v_mov_b32_e32 v81, v66
	s_waitcnt lgkmcnt(4)
	s_nop 0
	v_mfma_f32_32x32x16_bf16 v[82:97], v[206:209], v[98:101], v[66:81]
	ds_read_b128 v[206:209], v172 offset:4672
	s_waitcnt lgkmcnt(4)
	v_mfma_f32_32x32x16_bf16 v[66:81], v[210:213], v[98:101], v[66:81]
	ds_read_b128 v[210:213], v172 offset:96
	s_waitcnt lgkmcnt(4)
	v_mfma_f32_32x32x16_bf16 v[82:97], v[222:225], v[102:105], v[82:97]
	ds_read_b128 v[222:225], v172 offset:4704
	s_waitcnt lgkmcnt(4)
	v_mfma_f32_32x32x16_bf16 v[66:81], v[238:241], v[102:105], v[66:81]
	s_waitcnt lgkmcnt(3)
	v_mfma_f32_32x32x16_bf16 v[82:97], v[242:245], v[106:109], v[82:97]
	s_waitcnt lgkmcnt(2)
	v_mfma_f32_32x32x16_bf16 v[66:81], v[206:209], v[106:109], v[66:81]
	s_waitcnt lgkmcnt(1)
	v_mfma_f32_32x32x16_bf16 v[82:97], v[210:213], v[110:113], v[82:97]
	s_waitcnt lgkmcnt(0)
	v_mfma_f32_32x32x16_bf16 v[66:81], v[222:225], v[110:113], v[66:81]
	s_setprio 0
	s_nop 10
	v_max_f32_e32 v168, v66, v66
	v_max_f32_e32 v169, v82, v82
	v_max_f32_e32 v168, v169, v168
	v_max3_f32 v168, v168, v83, v67
	v_max3_f32 v168, v168, v84, v68
	v_max3_f32 v168, v168, v85, v69
	v_max3_f32 v168, v168, v86, v70
	v_max3_f32 v168, v168, v87, v71
	v_max3_f32 v168, v168, v88, v72
	v_max3_f32 v168, v168, v89, v73
	v_max3_f32 v168, v168, v90, v74
	v_max3_f32 v168, v168, v91, v75
	v_max3_f32 v168, v168, v92, v76
	v_max3_f32 v168, v168, v93, v77
	v_max3_f32 v168, v168, v94, v78
	v_max3_f32 v168, v168, v95, v79
	v_max3_f32 v168, v168, v96, v80
	v_max3_f32 v168, v168, v97, v81
	ds_bpermute_b32 v169, v147, v168
	s_mov_b32 s20, 0x41000000
	s_waitcnt lgkmcnt(0)
	v_max_f32_e32 v169, v169, v169
	v_max_f32_e32 v168, v168, v169
	v_cmp_lt_f32_e32 vcc, s20, v168
	s_cbranch_vccz .LBB0_269
	v_max_f32_e32 v168, v168, v168
	v_max_f32_e32 v168, 0, v168
	v_add_f32_e32 v169, v154, v168
	v_sub_f32_e32 v154, v169, v154
	v_mov_b32_e32 v170, v82
	v_mov_b32_e32 v171, v66
	v_mov_b32_e32 v82, v83
	v_mov_b32_e32 v83, v84
	v_mov_b32_e32 v66, v67
	v_mov_b32_e32 v67, v68
	v_pk_add_f32 v[172:173], v[82:83], v[154:155] op_sel_hi:[1,0] neg_lo:[0,1] neg_hi:[0,1]
	v_pk_add_f32 v[82:83], v[66:67], v[154:155] op_sel_hi:[1,0] neg_lo:[0,1] neg_hi:[0,1]
	v_mov_b32_e32 v66, v85
	v_mov_b32_e32 v67, v86
	v_pk_add_f32 v[174:175], v[66:67], v[154:155] op_sel_hi:[1,0] neg_lo:[0,1] neg_hi:[0,1]
	v_mov_b32_e32 v66, v69
	v_mov_b32_e32 v67, v70
	v_pk_add_f32 v[84:85], v[66:67], v[154:155] op_sel_hi:[1,0] neg_lo:[0,1] neg_hi:[0,1]
	v_mov_b32_e32 v66, v87
	v_mov_b32_e32 v67, v88
	v_pk_add_f32 v[176:177], v[66:67], v[154:155] op_sel_hi:[1,0] neg_lo:[0,1] neg_hi:[0,1]
	v_mov_b32_e32 v66, v71
	v_mov_b32_e32 v67, v72
	v_pk_add_f32 v[86:87], v[66:67], v[154:155] op_sel_hi:[1,0] neg_lo:[0,1] neg_hi:[0,1]
	v_mov_b32_e32 v66, v89
	v_mov_b32_e32 v67, v90
	v_pk_add_f32 v[178:179], v[66:67], v[154:155] op_sel_hi:[1,0] neg_lo:[0,1] neg_hi:[0,1]
	v_mov_b32_e32 v66, v73
	v_mov_b32_e32 v67, v74
	v_pk_add_f32 v[88:89], v[66:67], v[154:155] op_sel_hi:[1,0] neg_lo:[0,1] neg_hi:[0,1]
	v_mov_b32_e32 v66, v91
	v_mov_b32_e32 v67, v92
	v_pk_add_f32 v[180:181], v[66:67], v[154:155] op_sel_hi:[1,0] neg_lo:[0,1] neg_hi:[0,1]
	v_mov_b32_e32 v66, v75
	v_mov_b32_e32 v67, v76
	v_pk_add_f32 v[90:91], v[66:67], v[154:155] op_sel_hi:[1,0] neg_lo:[0,1] neg_hi:[0,1]
	v_mov_b32_e32 v66, v93
	v_mov_b32_e32 v67, v94
	v_exp_f32_e64 v168, -v154
	v_pk_add_f32 v[188:189], v[66:67], v[154:155] op_sel_hi:[1,0] neg_lo:[0,1] neg_hi:[0,1]
	v_mov_b32_e32 v66, v77
	v_mov_b32_e32 v67, v78
	v_pk_add_f32 v[92:93], v[66:67], v[154:155] op_sel_hi:[1,0] neg_lo:[0,1] neg_hi:[0,1]
	v_mov_b32_e32 v66, v95
	v_mov_b32_e32 v67, v96
	v_pk_add_f32 v[190:191], v[66:67], v[154:155] op_sel_hi:[1,0] neg_lo:[0,1] neg_hi:[0,1]
	v_mov_b32_e32 v66, v79
	v_mov_b32_e32 v67, v80
	v_pk_add_f32 v[170:171], v[170:171], v[154:155] op_sel_hi:[1,0] neg_lo:[0,1] neg_hi:[0,1]
	v_pk_add_f32 v[94:95], v[66:67], v[154:155] op_sel_hi:[1,0] neg_lo:[0,1] neg_hi:[0,1]
	v_pk_mul_f32 v[64:65], v[64:65], v[168:169] op_sel_hi:[1,0]
	v_pk_mul_f32 v[62:63], v[62:63], v[168:169] op_sel_hi:[1,0]
	v_pk_mul_f32 v[60:61], v[60:61], v[168:169] op_sel_hi:[1,0]
	v_pk_mul_f32 v[58:59], v[58:59], v[168:169] op_sel_hi:[1,0]
	v_pk_mul_f32 v[56:57], v[56:57], v[168:169] op_sel_hi:[1,0]
	v_pk_mul_f32 v[54:55], v[54:55], v[168:169] op_sel_hi:[1,0]
	v_pk_mul_f32 v[52:53], v[52:53], v[168:169] op_sel_hi:[1,0]
	v_pk_mul_f32 v[50:51], v[50:51], v[168:169] op_sel_hi:[1,0]
	v_pk_mul_f32 v[48:49], v[48:49], v[168:169] op_sel_hi:[1,0]
	v_pk_mul_f32 v[46:47], v[46:47], v[168:169] op_sel_hi:[1,0]
	v_pk_mul_f32 v[44:45], v[44:45], v[168:169] op_sel_hi:[1,0]
	v_pk_mul_f32 v[42:43], v[42:43], v[168:169] op_sel_hi:[1,0]
	v_pk_mul_f32 v[40:41], v[40:41], v[168:169] op_sel_hi:[1,0]
	v_pk_mul_f32 v[38:39], v[38:39], v[168:169] op_sel_hi:[1,0]
	v_pk_mul_f32 v[36:37], v[36:37], v[168:169] op_sel_hi:[1,0]
	v_pk_mul_f32 v[34:35], v[34:35], v[168:169] op_sel_hi:[1,0]
	v_pk_mul_f32 v[32:33], v[32:33], v[168:169] op_sel_hi:[1,0]
	v_pk_mul_f32 v[30:31], v[30:31], v[168:169] op_sel_hi:[1,0]
	v_pk_mul_f32 v[28:29], v[28:29], v[168:169] op_sel_hi:[1,0]
	v_pk_mul_f32 v[26:27], v[26:27], v[168:169] op_sel_hi:[1,0]
	v_pk_mul_f32 v[24:25], v[24:25], v[168:169] op_sel_hi:[1,0]
	v_pk_mul_f32 v[22:23], v[22:23], v[168:169] op_sel_hi:[1,0]
	v_pk_mul_f32 v[20:21], v[20:21], v[168:169] op_sel_hi:[1,0]
	v_pk_mul_f32 v[18:19], v[18:19], v[168:169] op_sel_hi:[1,0]
	v_pk_mul_f32 v[16:17], v[16:17], v[168:169] op_sel_hi:[1,0]
	v_pk_mul_f32 v[14:15], v[14:15], v[168:169] op_sel_hi:[1,0]
	v_pk_mul_f32 v[12:13], v[12:13], v[168:169] op_sel_hi:[1,0]
	v_pk_mul_f32 v[10:11], v[10:11], v[168:169] op_sel_hi:[1,0]
	v_pk_mul_f32 v[8:9], v[8:9], v[168:169] op_sel_hi:[1,0]
	v_pk_mul_f32 v[6:7], v[6:7], v[168:169] op_sel_hi:[1,0]
	v_pk_mul_f32 v[4:5], v[4:5], v[168:169] op_sel_hi:[1,0]
	v_pk_mul_f32 v[2:3], v[2:3], v[168:169] op_sel_hi:[1,0]
	v_sub_f32_e32 v97, v97, v154
	v_sub_f32_e32 v81, v81, v154
	v_mul_f32_e32 v185, v185, v168
	v_mov_b32_e32 v154, v169
	v_mov_b32_e32 v67, v82
	v_mov_b32_e32 v68, v83
	v_mov_b32_e32 v69, v84
	v_mov_b32_e32 v70, v85
	v_mov_b32_e32 v71, v86
	v_mov_b32_e32 v72, v87
	v_mov_b32_e32 v73, v88
	v_mov_b32_e32 v74, v89
	v_mov_b32_e32 v75, v90
	v_mov_b32_e32 v76, v91
	v_mov_b32_e32 v77, v92
	v_mov_b32_e32 v78, v93
	v_mov_b32_e32 v79, v94
	v_mov_b32_e32 v80, v95
	v_mov_b32_e32 v83, v172
	v_mov_b32_e32 v84, v173
	v_mov_b32_e32 v85, v174
	v_mov_b32_e32 v86, v175
	v_mov_b32_e32 v87, v176
	v_mov_b32_e32 v88, v177
	v_mov_b32_e32 v89, v178
	v_mov_b32_e32 v90, v179
	v_mov_b32_e32 v91, v180
	v_mov_b32_e32 v92, v181
	v_mov_b32_e32 v93, v188
	v_mov_b32_e32 v94, v189
	v_mov_b32_e32 v95, v190
	v_mov_b32_e32 v96, v191
	v_mov_b32_e32 v82, v170
	v_mov_b32_e32 v66, v171
.LBB0_269:
	v_exp_f32_e32 v180, v82
	v_exp_f32_e32 v181, v66
	v_exp_f32_e32 v178, v83
	v_exp_f32_e32 v179, v67
	v_exp_f32_e32 v176, v84
	v_exp_f32_e32 v177, v68
	v_exp_f32_e32 v174, v85
	v_exp_f32_e32 v175, v69
	v_exp_f32_e32 v172, v86
	v_exp_f32_e32 v173, v70
	v_exp_f32_e32 v170, v87
	v_exp_f32_e32 v171, v71
	v_exp_f32_e32 v168, v88
	v_exp_f32_e32 v169, v72
	v_exp_f32_e32 v88, v89
	v_exp_f32_e32 v89, v73
	v_exp_f32_e32 v86, v90
	v_exp_f32_e32 v87, v74
	v_exp_f32_e32 v84, v91
	v_exp_f32_e32 v85, v75
	v_exp_f32_e32 v82, v92
	v_exp_f32_e32 v83, v76
	v_exp_f32_e32 v74, v93
	v_exp_f32_e32 v75, v77
	v_exp_f32_e32 v72, v94
	v_exp_f32_e32 v73, v78
	v_exp_f32_e32 v70, v95
	v_exp_f32_e32 v71, v79
	v_exp_f32_e32 v68, v96
	v_exp_f32_e32 v69, v80
	v_exp_f32_e32 v66, v97
	v_exp_f32_e32 v67, v81
	v_cvt_pk_bf16_f32 v76, v180, v178
	v_cvt_pk_bf16_f32 v77, v176, v174
	v_cvt_pk_bf16_f32 v78, v172, v170
	v_cvt_pk_bf16_f32 v79, v168, v88
	v_cvt_pk_bf16_f32 v90, v86, v84
	v_cvt_pk_bf16_f32 v91, v82, v74
	v_cvt_pk_bf16_f32 v92, v72, v70
	v_cvt_pk_bf16_f32 v93, v68, v66
	v_cvt_pk_bf16_f32 v94, v181, v179
	v_cvt_pk_bf16_f32 v95, v177, v175
	v_cvt_pk_bf16_f32 v96, v173, v171
	v_cvt_pk_bf16_f32 v97, v169, v89
	v_cvt_pk_bf16_f32 v188, v87, v85
	v_cvt_pk_bf16_f32 v189, v83, v75
	v_cvt_pk_bf16_f32 v190, v73, v71
	v_cvt_pk_bf16_f32 v191, v69, v67
	s_setprio 1
	v_add3_u32 v80, s5, v150, v186
	v_add_u32_e32 v246, 0x4800, v80
	v_add_u32_e32 v247, 0x5800, v80
	v_add_u32_e32 v248, 0x6800, v80
	v_add_u32_e32 v249, 0x7800, v80
	ds_read2_b64 v[192:195], v246 offset0:0 offset1:2
	ds_read2_b64 v[206:209], v247 offset0:32 offset1:34
	ds_read2_b64 v[210:213], v248 offset0:64 offset1:66
	ds_read2_b64 v[222:225], v249 offset0:96 offset1:98
	s_waitcnt lgkmcnt(3)
	v_mfma_f32_32x32x16_bf16 v[50:65], v[192:195], v[76:79], v[50:65]
	ds_read2_b64 v[192:195], v246 offset0:4 offset1:6
	s_waitcnt lgkmcnt(3)
	v_mfma_f32_32x32x16_bf16 v[34:49], v[206:209], v[76:79], v[34:49]
	ds_read2_b64 v[206:209], v247 offset0:36 offset1:38
	s_waitcnt lgkmcnt(3)
	v_mfma_f32_32x32x16_bf16 v[18:33], v[210:213], v[76:79], v[18:33]
	ds_read2_b64 v[210:213], v248 offset0:68 offset1:70
	s_waitcnt lgkmcnt(3)
	v_mfma_f32_32x32x16_bf16 v[2:17], v[222:225], v[76:79], v[2:17]
	ds_read2_b64 v[222:225], v249 offset0:100 offset1:102
	s_waitcnt lgkmcnt(3)
	v_mfma_f32_32x32x16_bf16 v[50:65], v[192:195], v[90:93], v[50:65]
	ds_read2_b64 v[192:195], v246 offset0:8 offset1:10
	s_waitcnt lgkmcnt(3)
	v_mfma_f32_32x32x16_bf16 v[34:49], v[206:209], v[90:93], v[34:49]
	ds_read2_b64 v[206:209], v247 offset0:40 offset1:42
	s_waitcnt lgkmcnt(3)
	v_mfma_f32_32x32x16_bf16 v[18:33], v[210:213], v[90:93], v[18:33]
	ds_read2_b64 v[210:213], v248 offset0:72 offset1:74
	s_waitcnt lgkmcnt(3)
	v_mfma_f32_32x32x16_bf16 v[2:17], v[222:225], v[90:93], v[2:17]
	ds_read2_b64 v[222:225], v249 offset0:104 offset1:106
	s_waitcnt lgkmcnt(3)
	v_mfma_f32_32x32x16_bf16 v[50:65], v[192:195], v[94:97], v[50:65]
	ds_read2_b64 v[192:195], v246 offset0:12 offset1:14
	s_waitcnt lgkmcnt(3)
	v_mfma_f32_32x32x16_bf16 v[34:49], v[206:209], v[94:97], v[34:49]
	ds_read2_b64 v[206:209], v247 offset0:44 offset1:46
	s_waitcnt lgkmcnt(3)
	v_mfma_f32_32x32x16_bf16 v[18:33], v[210:213], v[94:97], v[18:33]
	ds_read2_b64 v[210:213], v248 offset0:76 offset1:78
	s_waitcnt lgkmcnt(3)
	v_mfma_f32_32x32x16_bf16 v[2:17], v[222:225], v[94:97], v[2:17]
	ds_read2_b64 v[222:225], v249 offset0:108 offset1:110
	s_waitcnt lgkmcnt(3)
	v_mfma_f32_32x32x16_bf16 v[50:65], v[192:195], v[188:191], v[50:65]
	s_waitcnt lgkmcnt(2)
	v_mfma_f32_32x32x16_bf16 v[34:49], v[206:209], v[188:191], v[34:49]
	s_waitcnt lgkmcnt(1)
	v_mfma_f32_32x32x16_bf16 v[18:33], v[210:213], v[188:191], v[18:33]
	s_waitcnt lgkmcnt(0)
	v_mfma_f32_32x32x16_bf16 v[2:17], v[222:225], v[188:191], v[2:17]
	s_setprio 0
	s_add_i32 s5, s4, -1
	s_cmp_ge_u32 s5, s77
	s_cbranch_scc1 .LBB0_266
	s_bitcmp1_b32 s5, 0
	s_cselect_b32 s5, 0x8c00, 0
	v_lshlrev_b32_e32 v76, 1, v153
	v_add3_u32 v76, s5, v76, v152
	s_waitcnt vmcnt(7)
	ds_write_b128 v76, v[114:117]
	s_waitcnt vmcnt(6)
	ds_write_b128 v76, v[118:121] offset:4608
	s_waitcnt vmcnt(5)
	ds_write_b128 v76, v[122:125] offset:9216
	s_waitcnt vmcnt(4)
	ds_write_b128 v76, v[126:129] offset:13824
	v_lshlrev_b32_e32 v76, 1, v182
	v_add3_u32 v76, s5, v76, v152
	v_add_u32_e32 v77, 0x4800, v76
	s_waitcnt vmcnt(3)
	ds_write2_b64 v77, v[130:131], v[132:133] offset1:1
	v_add_u32_e32 v77, 0x5900, v76
	s_waitcnt vmcnt(2)
	ds_write2_b64 v77, v[134:135], v[136:137] offset1:1
	v_add_u32_e32 v77, 0x6a00, v76
	v_add_u32_e32 v76, 0x7b00, v76
	s_cmp_ge_u32 s4, s77
	s_waitcnt vmcnt(1)
	ds_write2_b64 v77, v[138:139], v[140:141] offset1:1
	s_waitcnt vmcnt(0)
	ds_write2_b64 v76, v[142:143], v[144:145] offset1:1
	s_cbranch_scc1 .LBB0_266
	v_lshl_add_u64 v[76:77], v[156:157], 0, v[0:1]
	v_add_co_u32_e32 v78, vcc, 0xe42b000, v76
	s_nop 1
	v_addc_co_u32_e32 v79, vcc, 0, v77, vcc
	v_add_co_u32_e32 v76, vcc, 0xe42c000, v76
	s_nop 1
	v_addc_co_u32_e32 v77, vcc, 0, v77, vcc
	global_load_dwordx4 v[114:117], v[78:79], off
	global_load_dwordx4 v[118:121], v[76:77], off
	v_lshl_add_u64 v[76:77], v[158:159], 0, v[0:1]
	v_add_co_u32_e32 v78, vcc, 0xe42b000, v76
	s_nop 1
	v_addc_co_u32_e32 v79, vcc, 0, v77, vcc
	v_add_co_u32_e32 v76, vcc, 0xe42c000, v76
	s_nop 1
	v_addc_co_u32_e32 v77, vcc, 0, v77, vcc
	global_load_dwordx4 v[122:125], v[78:79], off
	global_load_dwordx4 v[126:129], v[76:77], off
	v_lshl_add_u64 v[76:77], v[160:161], 0, v[0:1]
	v_add_co_u32_e32 v76, vcc, 0xeca5000, v76
	s_nop 1
	v_addc_co_u32_e32 v77, vcc, 0, v77, vcc
	global_load_dwordx4 v[130:133], v[76:77], off offset:384
	v_lshl_add_u64 v[76:77], v[162:163], 0, v[0:1]
	v_add_co_u32_e32 v76, vcc, 0xeca5000, v76
	s_nop 1
	v_addc_co_u32_e32 v77, vcc, 0, v77, vcc
	global_load_dwordx4 v[134:137], v[76:77], off offset:384
	v_lshl_add_u64 v[76:77], v[164:165], 0, v[0:1]
	v_add_co_u32_e32 v76, vcc, 0xeca5000, v76
	s_nop 1
	v_addc_co_u32_e32 v77, vcc, 0, v77, vcc
	global_load_dwordx4 v[138:141], v[76:77], off offset:384
	v_lshl_add_u64 v[76:77], v[166:167], 0, v[0:1]
	v_add_co_u32_e32 v76, vcc, 0xeca5000, v76
	s_nop 1
	v_addc_co_u32_e32 v77, vcc, 0, v77, vcc
	global_load_dwordx4 v[142:145], v[76:77], off offset:384
	s_branch .LBB0_266
